# in-proj epilogue: hoist the 8 row-ss loads as well (on top of SwiGLU hoist)
# speedup vs baseline: 1.0082x; 1.0004x over previous
; __device__ __forceinline__ unsigned cvt_pk_bf16(float lo, float hi) { unsigned r; asm volatile("v_cvt_pk_bf16_f32 %0, %1, %2" : "=v"(r) : "v"(lo), "v"(hi)); return r; }
;     __device__ __forceinline__ void operator()(const AccT& acc, const Unit& u, int wr, int wc, int fr, int fq) const {
;         const int row0 = u.pm * BM + wr * 64 + fr, col0 = u.pn * BM + wc * 32 + 8 * fq;
; #pragma unroll
;         for (int ai = 0; ai < 2; ++ai)
; #pragma unroll
;             for (int m = 0; m < 4; ++m) {
;                 const int row = row0 + ai * HALF + m * 16;
;                 const float rs = rsqrtf(ss[row] * (1.f / 1024.f) + EPS);
; #pragma unroll
;                 for (int bj = 0; bj < 2; ++bj) {
;                     const int col = col0 + bj * HALF;
;                     const f32x4 v0 = acc[ai][bj][m][0] * rs, v1 = acc[ai][bj][m][1] * rs;
;                     u32x4 w; w.x = cvt_pk_bf16(v0[0], v0[1]); w.y = cvt_pk_bf16(v0[2], v0[3]); w.z = cvt_pk_bf16(v1[0], v1[1]); w.w = cvt_pk_bf16(v1[2], v1[3]);
;                     *(u32x4*)(P + (size_t)row * LDP + col) = w;
;                     if (col >= C_SM && col < C_SM + 16) { float* s = SM + (size_t)row * 16 + (col - C_SM); *(f32x4*)s = v0; *(f32x4*)(s + 4) = v1; }
;                 }
;             }
;     }
.LBB0_426:
	v_lshl_add_u32 v148, s22, 8, v129
	v_ashrrev_i32_e32 v149, 31, v148
	v_lshl_add_u64 v[150:151], v[148:149], 2, s[0:1]
	global_load_dword v147, v[150:151], off
	global_load_dword v233, v[150:151], off offset:64
	global_load_dword v234, v[150:151], off offset:128
	global_load_dword v235, v[150:151], off offset:192
	global_load_dword v236, v[150:151], off offset:512
	global_load_dword v237, v[150:151], off offset:576
	global_load_dword v238, v[150:151], off offset:640
	global_load_dword v239, v[150:151], off offset:704
	s_lshl_b32 s15, s6, 8
	v_mov_b64_e32 v[152:153], s[44:45]
	v_or_b32_e32 v146, s15, v159
	v_mad_i64_i32 v[152:153], s[6:7], v148, s86, v[152:153]
	v_bitop3_b32 v155, s15, v167, v159 bitop3:0xc8
	v_cmp_eq_u32_e64 s[6:7], s87, v155
	s_waitcnt vmcnt(0)
	v_fmamk_f32 v147, v147, 0x3a800000, v166
	v_mul_f32_e32 v154, 0x4b800000, v147
	v_cmp_gt_f32_e32 vcc, s85, v147
	s_nop 1
	v_cndmask_b32_e32 v147, v147, v154, vcc
	v_rsq_f32_e32 v154, v147
	v_ashrrev_i32_e32 v147, 31, v146
	v_lshl_add_u64 v[152:153], v[146:147], 1, v[152:153]
	v_mul_f32_e32 v168, 0x45800000, v154
	v_cndmask_b32_e32 v154, v154, v168, vcc
	v_pk_mul_f32 v[126:127], v[126:127], v[154:155] op_sel_hi:[1,0]
	v_pk_mul_f32 v[124:125], v[124:125], v[154:155] op_sel_hi:[1,0]
	v_pk_mul_f32 v[122:123], v[122:123], v[154:155] op_sel_hi:[1,0]
	v_pk_mul_f32 v[120:121], v[120:121], v[154:155] op_sel_hi:[1,0]
	v_cvt_pk_bf16_f32 v168, v124, v125
	v_cvt_pk_bf16_f32 v169, v126, v127
	s_nop 0
	v_cvt_pk_bf16_f32 v170, v120, v121
	v_cvt_pk_bf16_f32 v171, v122, v123
	global_store_dwordx4 v[152:153], v[168:171], off
	s_and_saveexec_b64 s[22:23], s[6:7]
	s_cbranch_execz .LBB0_428
	v_lshlrev_b64 v[168:169], 6, v[148:149]
	v_lshl_add_u64 v[168:169], s[58:59], 0, v[168:169]
	v_lshl_add_u64 v[168:169], v[146:147], 2, v[168:169]
	v_add_co_u32_e32 v168, vcc, 0xffffc000, v168
	s_nop 1
	v_addc_co_u32_e32 v169, vcc, -1, v169, vcc
	global_store_dwordx4 v[168:169], v[124:127], off offset:-3328
	global_store_dwordx4 v[168:169], v[120:123], off offset:-3312
.LBB0_428:
	s_or_b64 exec, exec, s[22:23]
	v_mov_b32_e32 v155, v154
	v_mov_b32_e32 v120, v154
	v_mov_b32_e32 v121, v154
	v_pk_mul_f32 v[118:119], v[118:119], v[120:121]
	v_pk_mul_f32 v[116:117], v[116:117], v[154:155]
	v_pk_mul_f32 v[120:121], v[114:115], v[120:121]
	v_pk_mul_f32 v[114:115], v[112:113], v[154:155]
	v_cvt_pk_bf16_f32 v112, v116, v117
	v_cvt_pk_bf16_f32 v113, v118, v119
	s_nop 0
	v_cvt_pk_bf16_f32 v114, v114, v115
	v_cvt_pk_bf16_f32 v115, v120, v121
	global_store_dwordx4 v[152:153], v[112:115], off offset:256
	s_nop 1
	v_or_b32_e32 v112, 16, v148
	v_ashrrev_i32_e32 v113, 31, v112
	v_lshl_add_u64 v[114:115], v[112:113], 2, s[0:1]
	s_nop 0
	s_nop 0
	v_fmamk_f32 v114, v233, 0x3a800000, v166
	v_mul_f32_e32 v115, 0x4b800000, v114
	v_cmp_gt_f32_e32 vcc, s85, v114
	s_nop 1
	v_cndmask_b32_e32 v114, v114, v115, vcc
	v_rsq_f32_e32 v116, v114
	v_mov_b64_e32 v[114:115], s[44:45]
	v_mad_i64_i32 v[114:115], s[22:23], v112, s86, v[114:115]
	v_mul_f32_e32 v117, 0x45800000, v116
	v_cndmask_b32_e32 v116, v116, v117, vcc
	v_pk_mul_f32 v[110:111], v[110:111], v[116:117] op_sel_hi:[1,0]
	v_pk_mul_f32 v[108:109], v[108:109], v[116:117] op_sel_hi:[1,0]
	v_pk_mul_f32 v[106:107], v[106:107], v[116:117] op_sel_hi:[1,0]
	v_pk_mul_f32 v[104:105], v[104:105], v[116:117] op_sel_hi:[1,0]
	v_lshl_add_u64 v[114:115], v[146:147], 1, v[114:115]
	v_cvt_pk_bf16_f32 v118, v108, v109
	v_cvt_pk_bf16_f32 v119, v110, v111
	v_cvt_pk_bf16_f32 v120, v104, v105
	v_cvt_pk_bf16_f32 v121, v106, v107
	global_store_dwordx4 v[114:115], v[118:121], off
	s_and_saveexec_b64 s[22:23], s[6:7]
	s_cbranch_execz .LBB0_430
	v_lshlrev_b64 v[112:113], 6, v[112:113]
	v_lshl_add_u64 v[112:113], s[58:59], 0, v[112:113]
	v_lshl_add_u64 v[112:113], v[146:147], 2, v[112:113]
	v_add_co_u32_e32 v112, vcc, 0xffffc000, v112
	s_nop 1
	v_addc_co_u32_e32 v113, vcc, -1, v113, vcc
	global_store_dwordx4 v[112:113], v[108:111], off offset:-3328
	global_store_dwordx4 v[112:113], v[104:107], off offset:-3312
.LBB0_430:
	s_or_b64 exec, exec, s[22:23]
	v_mov_b32_e32 v117, v116
	v_mov_b32_e32 v104, v116
	v_mov_b32_e32 v105, v116
	v_pk_mul_f32 v[102:103], v[102:103], v[104:105]
	v_pk_mul_f32 v[100:101], v[100:101], v[116:117]
	v_pk_mul_f32 v[104:105], v[98:99], v[104:105]
	v_pk_mul_f32 v[98:99], v[96:97], v[116:117]
	v_cvt_pk_bf16_f32 v96, v100, v101
	v_cvt_pk_bf16_f32 v97, v102, v103
	s_nop 0
	v_cvt_pk_bf16_f32 v98, v98, v99
	v_cvt_pk_bf16_f32 v99, v104, v105
	global_store_dwordx4 v[114:115], v[96:99], off offset:256
	s_nop 1
	v_or_b32_e32 v96, 32, v148
	v_ashrrev_i32_e32 v97, 31, v96
	v_lshl_add_u64 v[98:99], v[96:97], 2, s[0:1]
	s_nop 0
	s_nop 0
	v_fmamk_f32 v98, v234, 0x3a800000, v166
	v_mul_f32_e32 v99, 0x4b800000, v98
	v_cmp_gt_f32_e32 vcc, s85, v98
	s_nop 1
	v_cndmask_b32_e32 v98, v98, v99, vcc
	v_rsq_f32_e32 v100, v98
	v_mov_b64_e32 v[98:99], s[44:45]
	v_mad_i64_i32 v[98:99], s[22:23], v96, s86, v[98:99]
	v_mul_f32_e32 v101, 0x45800000, v100
	v_cndmask_b32_e32 v100, v100, v101, vcc
	v_pk_mul_f32 v[94:95], v[94:95], v[100:101] op_sel_hi:[1,0]
	v_pk_mul_f32 v[92:93], v[92:93], v[100:101] op_sel_hi:[1,0]
	v_pk_mul_f32 v[90:91], v[90:91], v[100:101] op_sel_hi:[1,0]
	v_pk_mul_f32 v[88:89], v[88:89], v[100:101] op_sel_hi:[1,0]
	v_lshl_add_u64 v[98:99], v[146:147], 1, v[98:99]
	v_cvt_pk_bf16_f32 v102, v92, v93
	v_cvt_pk_bf16_f32 v103, v94, v95
	v_cvt_pk_bf16_f32 v104, v88, v89
	v_cvt_pk_bf16_f32 v105, v90, v91
	global_store_dwordx4 v[98:99], v[102:105], off
	s_and_saveexec_b64 s[22:23], s[6:7]
	s_cbranch_execz .LBB0_432
	v_lshlrev_b64 v[96:97], 6, v[96:97]
	v_lshl_add_u64 v[96:97], s[58:59], 0, v[96:97]
	v_lshl_add_u64 v[96:97], v[146:147], 2, v[96:97]
	v_add_co_u32_e32 v96, vcc, 0xffffc000, v96
	s_nop 1
	v_addc_co_u32_e32 v97, vcc, -1, v97, vcc
	global_store_dwordx4 v[96:97], v[92:95], off offset:-3328
	global_store_dwordx4 v[96:97], v[88:91], off offset:-3312
; __device__ __forceinline__ unsigned cvt_pk_bf16(float lo, float hi) { unsigned r; asm volatile("v_cvt_pk_bf16_f32 %0, %1, %2" : "=v"(r) : "v"(lo), "v"(hi)); return r; }
;     __device__ __forceinline__ void operator()(const AccT& acc, const Unit& u, int wr, int wc, int fr, int fq) const {
;         const int row0 = u.pm * BM + wr * 64 + fr, col0 = u.pn * BM + wc * 32 + 8 * fq;
; #pragma unroll
;         for (int ai = 0; ai < 2; ++ai)
; #pragma unroll
;             for (int m = 0; m < 4; ++m) {
;                 const int row = row0 + ai * HALF + m * 16;
;                 const float rs = rsqrtf(ss[row] * (1.f / 1024.f) + EPS);
; #pragma unroll
;                 for (int bj = 0; bj < 2; ++bj) {
;                     const int col = col0 + bj * HALF;
;                     const f32x4 v0 = acc[ai][bj][m][0] * rs, v1 = acc[ai][bj][m][1] * rs;
;                     u32x4 w; w.x = cvt_pk_bf16(v0[0], v0[1]); w.y = cvt_pk_bf16(v0[2], v0[3]); w.z = cvt_pk_bf16(v1[0], v1[1]); w.w = cvt_pk_bf16(v1[2], v1[3]);
;                     *(u32x4*)(P + (size_t)row * LDP + col) = w;
;                     if (col >= C_SM && col < C_SM + 16) { float* s = SM + (size_t)row * 16 + (col - C_SM); *(f32x4*)s = v0; *(f32x4*)(s + 4) = v1; }
;                 }
;             }
;     }
.LBB0_432:
	s_or_b64 exec, exec, s[22:23]
	v_mov_b32_e32 v101, v100
	v_mov_b32_e32 v88, v100
	v_mov_b32_e32 v89, v100
	v_pk_mul_f32 v[86:87], v[86:87], v[88:89]
	v_pk_mul_f32 v[84:85], v[84:85], v[100:101]
	v_pk_mul_f32 v[88:89], v[82:83], v[88:89]
	v_pk_mul_f32 v[82:83], v[80:81], v[100:101]
	v_cvt_pk_bf16_f32 v80, v84, v85
	v_cvt_pk_bf16_f32 v81, v86, v87
	s_nop 0
	v_cvt_pk_bf16_f32 v82, v82, v83
	v_cvt_pk_bf16_f32 v83, v88, v89
	global_store_dwordx4 v[98:99], v[80:83], off offset:256
	s_nop 1
	v_or_b32_e32 v80, 48, v148
	v_ashrrev_i32_e32 v81, 31, v80
	v_lshl_add_u64 v[82:83], v[80:81], 2, s[0:1]
	s_nop 0
	s_nop 0
	v_fmamk_f32 v82, v235, 0x3a800000, v166
	v_mul_f32_e32 v83, 0x4b800000, v82
	v_cmp_gt_f32_e32 vcc, s85, v82
	s_nop 1
	v_cndmask_b32_e32 v82, v82, v83, vcc
	v_rsq_f32_e32 v84, v82
	v_mov_b64_e32 v[82:83], s[44:45]
	v_mad_i64_i32 v[82:83], s[22:23], v80, s86, v[82:83]
	v_mul_f32_e32 v85, 0x45800000, v84
	v_cndmask_b32_e32 v84, v84, v85, vcc
	v_pk_mul_f32 v[78:79], v[78:79], v[84:85] op_sel_hi:[1,0]
	v_pk_mul_f32 v[76:77], v[76:77], v[84:85] op_sel_hi:[1,0]
	v_pk_mul_f32 v[74:75], v[74:75], v[84:85] op_sel_hi:[1,0]
	v_pk_mul_f32 v[72:73], v[72:73], v[84:85] op_sel_hi:[1,0]
	v_lshl_add_u64 v[82:83], v[146:147], 1, v[82:83]
	v_cvt_pk_bf16_f32 v86, v76, v77
	v_cvt_pk_bf16_f32 v87, v78, v79
	v_cvt_pk_bf16_f32 v88, v72, v73
	v_cvt_pk_bf16_f32 v89, v74, v75
	global_store_dwordx4 v[82:83], v[86:89], off
	s_and_saveexec_b64 s[22:23], s[6:7]
	s_cbranch_execz .LBB0_434
	v_lshlrev_b64 v[80:81], 6, v[80:81]
	v_lshl_add_u64 v[80:81], s[58:59], 0, v[80:81]
	v_lshl_add_u64 v[80:81], v[146:147], 2, v[80:81]
	v_add_co_u32_e32 v80, vcc, 0xffffc000, v80
	s_nop 1
	v_addc_co_u32_e32 v81, vcc, -1, v81, vcc
	global_store_dwordx4 v[80:81], v[76:79], off offset:-3328
	global_store_dwordx4 v[80:81], v[72:75], off offset:-3312
.LBB0_434:
	s_or_b64 exec, exec, s[22:23]
	v_mov_b32_e32 v85, v84
	v_mov_b32_e32 v72, v84
	v_mov_b32_e32 v73, v84
	v_pk_mul_f32 v[70:71], v[70:71], v[72:73]
	v_pk_mul_f32 v[72:73], v[66:67], v[72:73]
	v_pk_mul_f32 v[66:67], v[64:65], v[84:85]
	v_pk_mul_f32 v[68:69], v[68:69], v[84:85]
	s_nop 0
	v_cvt_pk_bf16_f32 v64, v68, v69
	v_cvt_pk_bf16_f32 v65, v70, v71
	v_cvt_pk_bf16_f32 v66, v66, v67
	v_cvt_pk_bf16_f32 v67, v72, v73
	global_store_dwordx4 v[82:83], v[64:67], off offset:256
	s_nop 0
	s_nop 0
	v_add_u32_e32 v64, 0x80, v148
	s_nop 0
	v_fmamk_f32 v65, v236, 0x3a800000, v166
	v_mul_f32_e32 v66, 0x4b800000, v65
	v_cmp_gt_f32_e32 vcc, s85, v65
	s_nop 1
	v_cndmask_b32_e32 v65, v65, v66, vcc
	v_rsq_f32_e32 v65, v65
	v_mov_b64_e32 v[66:67], s[44:45]
	v_mad_i64_i32 v[66:67], s[22:23], v64, s86, v[66:67]
	v_mul_f32_e32 v68, 0x45800000, v65
	v_cndmask_b32_e32 v68, v65, v68, vcc
	v_pk_mul_f32 v[62:63], v[62:63], v[68:69] op_sel_hi:[1,0]
	v_pk_mul_f32 v[60:61], v[60:61], v[68:69] op_sel_hi:[1,0]
	v_pk_mul_f32 v[58:59], v[58:59], v[68:69] op_sel_hi:[1,0]
	v_pk_mul_f32 v[56:57], v[56:57], v[68:69] op_sel_hi:[1,0]
	v_lshl_add_u64 v[66:67], v[146:147], 1, v[66:67]
	v_cvt_pk_bf16_f32 v70, v60, v61
	v_cvt_pk_bf16_f32 v71, v62, v63
	v_cvt_pk_bf16_f32 v72, v56, v57
	v_cvt_pk_bf16_f32 v73, v58, v59
	global_store_dwordx4 v[66:67], v[70:73], off
	s_and_saveexec_b64 s[22:23], s[6:7]
	s_cbranch_execz .LBB0_436
	v_ashrrev_i32_e32 v65, 31, v64
	v_lshlrev_b64 v[64:65], 6, v[64:65]
	v_lshl_add_u64 v[64:65], s[58:59], 0, v[64:65]
	v_lshl_add_u64 v[64:65], v[146:147], 2, v[64:65]
	v_add_co_u32_e32 v64, vcc, 0xffffc000, v64
	s_nop 1
	v_addc_co_u32_e32 v65, vcc, -1, v65, vcc
	global_store_dwordx4 v[64:65], v[60:63], off offset:-3328
	global_store_dwordx4 v[64:65], v[56:59], off offset:-3312
; __device__ __forceinline__ unsigned cvt_pk_bf16(float lo, float hi) { unsigned r; asm volatile("v_cvt_pk_bf16_f32 %0, %1, %2" : "=v"(r) : "v"(lo), "v"(hi)); return r; }
;     __device__ __forceinline__ void operator()(const AccT& acc, const Unit& u, int wr, int wc, int fr, int fq) const {
;         const int row0 = u.pm * BM + wr * 64 + fr, col0 = u.pn * BM + wc * 32 + 8 * fq;
; #pragma unroll
;         for (int ai = 0; ai < 2; ++ai)
; #pragma unroll
;             for (int m = 0; m < 4; ++m) {
;                 const int row = row0 + ai * HALF + m * 16;
;                 const float rs = rsqrtf(ss[row] * (1.f / 1024.f) + EPS);
; #pragma unroll
;                 for (int bj = 0; bj < 2; ++bj) {
;                     const int col = col0 + bj * HALF;
;                     const f32x4 v0 = acc[ai][bj][m][0] * rs, v1 = acc[ai][bj][m][1] * rs;
;                     u32x4 w; w.x = cvt_pk_bf16(v0[0], v0[1]); w.y = cvt_pk_bf16(v0[2], v0[3]); w.z = cvt_pk_bf16(v1[0], v1[1]); w.w = cvt_pk_bf16(v1[2], v1[3]);
;                     *(u32x4*)(P + (size_t)row * LDP + col) = w;
;                     if (col >= C_SM && col < C_SM + 16) { float* s = SM + (size_t)row * 16 + (col - C_SM); *(f32x4*)s = v0; *(f32x4*)(s + 4) = v1; }
;                 }
;             }
;     }
.LBB0_436:
	s_or_b64 exec, exec, s[22:23]
	v_mov_b32_e32 v69, v68
	v_mov_b32_e32 v56, v68
	v_mov_b32_e32 v57, v68
	v_pk_mul_f32 v[54:55], v[54:55], v[56:57]
	v_pk_mul_f32 v[56:57], v[50:51], v[56:57]
	v_pk_mul_f32 v[50:51], v[48:49], v[68:69]
	v_pk_mul_f32 v[52:53], v[52:53], v[68:69]
	s_nop 0
	v_cvt_pk_bf16_f32 v48, v52, v53
	v_cvt_pk_bf16_f32 v49, v54, v55
	v_cvt_pk_bf16_f32 v50, v50, v51
	v_cvt_pk_bf16_f32 v51, v56, v57
	global_store_dwordx4 v[66:67], v[48:51], off offset:256
	s_nop 0
	s_nop 0
	v_add_u32_e32 v48, 0x90, v148
	s_nop 0
	v_fmamk_f32 v49, v237, 0x3a800000, v166
	v_mul_f32_e32 v50, 0x4b800000, v49
	v_cmp_gt_f32_e32 vcc, s85, v49
	s_nop 1
	v_cndmask_b32_e32 v49, v49, v50, vcc
	v_rsq_f32_e32 v49, v49
	v_mov_b64_e32 v[50:51], s[44:45]
	v_mad_i64_i32 v[50:51], s[22:23], v48, s86, v[50:51]
	v_mul_f32_e32 v52, 0x45800000, v49
	v_cndmask_b32_e32 v52, v49, v52, vcc
	v_pk_mul_f32 v[46:47], v[46:47], v[52:53] op_sel_hi:[1,0]
	v_pk_mul_f32 v[44:45], v[44:45], v[52:53] op_sel_hi:[1,0]
	v_pk_mul_f32 v[42:43], v[42:43], v[52:53] op_sel_hi:[1,0]
	v_pk_mul_f32 v[40:41], v[40:41], v[52:53] op_sel_hi:[1,0]
	v_lshl_add_u64 v[50:51], v[146:147], 1, v[50:51]
	v_cvt_pk_bf16_f32 v54, v44, v45
	v_cvt_pk_bf16_f32 v55, v46, v47
	v_cvt_pk_bf16_f32 v56, v40, v41
	v_cvt_pk_bf16_f32 v57, v42, v43
	global_store_dwordx4 v[50:51], v[54:57], off
	s_and_saveexec_b64 s[22:23], s[6:7]
	s_cbranch_execz .LBB0_438
	v_ashrrev_i32_e32 v49, 31, v48
	v_lshlrev_b64 v[48:49], 6, v[48:49]
	v_lshl_add_u64 v[48:49], s[58:59], 0, v[48:49]
	v_lshl_add_u64 v[48:49], v[146:147], 2, v[48:49]
	v_add_co_u32_e32 v48, vcc, 0xffffc000, v48
	s_nop 1
	v_addc_co_u32_e32 v49, vcc, -1, v49, vcc
	global_store_dwordx4 v[48:49], v[44:47], off offset:-3328
	global_store_dwordx4 v[48:49], v[40:43], off offset:-3312
.LBB0_438:
	s_or_b64 exec, exec, s[22:23]
	v_mov_b32_e32 v53, v52
	v_mov_b32_e32 v40, v52
	v_mov_b32_e32 v41, v52
	v_pk_mul_f32 v[38:39], v[38:39], v[40:41]
	v_pk_mul_f32 v[40:41], v[34:35], v[40:41]
	v_pk_mul_f32 v[34:35], v[32:33], v[52:53]
	v_pk_mul_f32 v[36:37], v[36:37], v[52:53]
	s_nop 0
	v_cvt_pk_bf16_f32 v32, v36, v37
	v_cvt_pk_bf16_f32 v33, v38, v39
	v_cvt_pk_bf16_f32 v34, v34, v35
	v_cvt_pk_bf16_f32 v35, v40, v41
	global_store_dwordx4 v[50:51], v[32:35], off offset:256
	s_nop 0
	s_nop 0
	v_add_u32_e32 v32, 0xa0, v148
	s_nop 0
	v_fmamk_f32 v33, v238, 0x3a800000, v166
	v_mul_f32_e32 v34, 0x4b800000, v33
	v_cmp_gt_f32_e32 vcc, s85, v33
	s_nop 1
	v_cndmask_b32_e32 v33, v33, v34, vcc
	v_rsq_f32_e32 v33, v33
	v_mov_b64_e32 v[34:35], s[44:45]
	v_mad_i64_i32 v[34:35], s[22:23], v32, s86, v[34:35]
	v_mul_f32_e32 v36, 0x45800000, v33
	v_cndmask_b32_e32 v36, v33, v36, vcc
	v_pk_mul_f32 v[30:31], v[30:31], v[36:37] op_sel_hi:[1,0]
	v_pk_mul_f32 v[28:29], v[28:29], v[36:37] op_sel_hi:[1,0]
	v_pk_mul_f32 v[26:27], v[26:27], v[36:37] op_sel_hi:[1,0]
	v_pk_mul_f32 v[24:25], v[24:25], v[36:37] op_sel_hi:[1,0]
	v_lshl_add_u64 v[34:35], v[146:147], 1, v[34:35]
	v_cvt_pk_bf16_f32 v38, v28, v29
	v_cvt_pk_bf16_f32 v39, v30, v31
	v_cvt_pk_bf16_f32 v40, v24, v25
	v_cvt_pk_bf16_f32 v41, v26, v27
	global_store_dwordx4 v[34:35], v[38:41], off
	s_and_saveexec_b64 s[22:23], s[6:7]
	s_cbranch_execz .LBB0_440
	v_ashrrev_i32_e32 v33, 31, v32
	v_lshlrev_b64 v[32:33], 6, v[32:33]
	v_lshl_add_u64 v[32:33], s[58:59], 0, v[32:33]
	v_lshl_add_u64 v[32:33], v[146:147], 2, v[32:33]
	v_add_co_u32_e32 v32, vcc, 0xffffc000, v32
	s_nop 1
	v_addc_co_u32_e32 v33, vcc, -1, v33, vcc
	global_store_dwordx4 v[32:33], v[28:31], off offset:-3328
	global_store_dwordx4 v[32:33], v[24:27], off offset:-3312
.LBB0_440:
	s_or_b64 exec, exec, s[22:23]
	v_mov_b32_e32 v37, v36
	v_mov_b32_e32 v24, v36
	v_mov_b32_e32 v25, v36
	v_pk_mul_f32 v[22:23], v[22:23], v[24:25]
	v_pk_mul_f32 v[24:25], v[18:19], v[24:25]
	v_pk_mul_f32 v[18:19], v[16:17], v[36:37]
	v_pk_mul_f32 v[20:21], v[20:21], v[36:37]
	s_nop 0
	v_cvt_pk_bf16_f32 v16, v20, v21
	v_cvt_pk_bf16_f32 v17, v22, v23
	v_cvt_pk_bf16_f32 v18, v18, v19
	v_cvt_pk_bf16_f32 v19, v24, v25
	global_store_dwordx4 v[34:35], v[16:19], off offset:256
	s_nop 0
	s_nop 0
	v_add_u32_e32 v16, 0xb0, v148
	s_nop 0
	v_fmamk_f32 v17, v239, 0x3a800000, v166
	v_mul_f32_e32 v18, 0x4b800000, v17
	v_cmp_gt_f32_e32 vcc, s85, v17
	s_nop 1
	v_cndmask_b32_e32 v17, v17, v18, vcc
	v_rsq_f32_e32 v17, v17
	v_mov_b64_e32 v[18:19], s[44:45]
	v_mad_i64_i32 v[18:19], s[22:23], v16, s86, v[18:19]
	v_mul_f32_e32 v20, 0x45800000, v17
	v_cndmask_b32_e32 v20, v17, v20, vcc
	v_pk_mul_f32 v[14:15], v[14:15], v[20:21] op_sel_hi:[1,0]
	v_pk_mul_f32 v[12:13], v[12:13], v[20:21] op_sel_hi:[1,0]
	v_pk_mul_f32 v[10:11], v[10:11], v[20:21] op_sel_hi:[1,0]
	v_pk_mul_f32 v[8:9], v[8:9], v[20:21] op_sel_hi:[1,0]
	v_lshl_add_u64 v[18:19], v[146:147], 1, v[18:19]
	v_cvt_pk_bf16_f32 v22, v12, v13
	v_cvt_pk_bf16_f32 v23, v14, v15
	v_cvt_pk_bf16_f32 v24, v8, v9
	v_cvt_pk_bf16_f32 v25, v10, v11
	global_store_dwordx4 v[18:19], v[22:25], off
	s_and_saveexec_b64 s[22:23], s[6:7]
	s_cbranch_execz .LBB0_442
	v_ashrrev_i32_e32 v17, 31, v16
	v_lshlrev_b64 v[16:17], 6, v[16:17]
	v_lshl_add_u64 v[16:17], s[58:59], 0, v[16:17]
	v_lshl_add_u64 v[16:17], v[146:147], 2, v[16:17]
	v_add_co_u32_e32 v16, vcc, 0xffffc000, v16
	s_nop 1
	v_addc_co_u32_e32 v17, vcc, -1, v17, vcc
	global_store_dwordx4 v[16:17], v[12:15], off offset:-3328
	global_store_dwordx4 v[16:17], v[8:11], off offset:-3312
